# bisection: first-group partial count with early accept when the partial count already reaches 256 (second exact round otherwise)
# speedup vs baseline: 1.0276x; 1.0053x over previous
; #define PAIR_XCHG(SLOT, TAG, MINE, OTHER) do { const unsigned tg_ = (seq << 8) | (unsigned)(TAG); if (lane == 0) xw[w * 4 + (SLOT)] = ((MINE) << 16) | tg_; \
;             unsigned v_; do { v_ = xw[(w ^ 1) * 4 + (SLOT)]; } while ((v_ & 0xffffu) != tg_); OTHER = v_ >> 16; } while (0)
; __device__ __forceinline__ void attn_item(const Ptrs& P, unsigned char* lds, int b, int tq0, int tid) {
;     ...
;             const unsigned cand = th | (1u << bit); unsigned cnt = 0, oth;
; #pragma unroll
;             for (int k = 0; k < 4; ++k) if (16 * k < nact) {
; #pragma unroll
;                 for (int r = 16 * k; r < 16 * k + 16; ++r) cnt += (unsigned)__popcll(__ballot(k2[r] >= cand)); }
;             PAIR_XCHG(bit & 1, 1 + bit, cnt, oth);
;             cnt += oth;
;             if (cnt >= 256u) th = cand;
;             if (cnt == 256u) break;
.Lbis_mspin:
	ds_read_b32 v27, v37
	s_waitcnt lgkmcnt(0)
	v_readfirstlane_b32 s13, v27
	s_nop 3
	s_and_b32 s89, s13, 0xffff
	s_cmp_eq_u32 s89, s12
	s_cbranch_scc0 .Lbis_mspin
	s_lshr_b32 s13, s13, 16
	s_max_u32 s84, s84, s13
	s_mov_b32 s85, 0
	s_mov_b32 s96, 0
	s_mov_b32 s97, 0xffff
	v_readfirstlane_b32 s93, v125
	s_mov_b32 s87, s74
.Lbis_loop:
	s_lshl_b32 s12, 1, s75
	s_or_b32 s12, s85, s12
	s_lshr_b32 s13, s12, 16
	s_cmp_gt_u32 s13, s84
	s_cbranch_scc1 .Lbis_next
	v_mov_b32_e32 v24, s12
	v_mov_b32_e32 v25, 0
	v_add_u32_e32 v26, -1, v24
	s_mov_b32 s90, 0
	s_cmp_lt_u32 s97, 0x800
	s_cbranch_scc1 .Lbis_full
	s_cmp_lt_u32 s93, 64
	s_cbranch_scc1 .Lbis_full
	v_med3_u32 v38, v6, v26, v24
	v_med3_u32 v39, v95, v26, v24
	v_add3_u32 v25, v25, v38, v39
	v_med3_u32 v40, v94, v26, v24
	v_med3_u32 v41, v93, v26, v24
	v_add3_u32 v25, v25, v40, v41
	v_med3_u32 v42, v92, v26, v24
	v_med3_u32 v43, v91, v26, v24
	v_add3_u32 v25, v25, v42, v43
	v_med3_u32 v44, v90, v26, v24
	v_med3_u32 v45, v89, v26, v24
	v_add3_u32 v25, v25, v44, v45
	v_med3_u32 v38, v88, v26, v24
	v_med3_u32 v39, v87, v26, v24
	v_add3_u32 v25, v25, v38, v39
	v_med3_u32 v40, v86, v26, v24
	v_med3_u32 v41, v85, v26, v24
	v_add3_u32 v25, v25, v40, v41
	v_med3_u32 v42, v84, v26, v24
	v_med3_u32 v43, v83, v26, v24
	v_add3_u32 v25, v25, v42, v43
	v_med3_u32 v44, v82, v26, v24
	v_med3_u32 v45, v81, v26, v24
	v_add3_u32 v25, v25, v44, v45
	s_mov_b32 s90, 16
	s_sub_u32 s91, s12, 1
	s_mul_i32 s91, s91, s90
	v_subrev_u32_e32 v25, s91, v25
	s_add_i32 s13, s75, 1
	s_or_b32 s13, s86, s13
	v_add_u32_dpp v25, v25, v25 row_ror:1 row_mask:0xf bank_mask:0xf
	s_nop 1
	v_add_u32_dpp v25, v25, v25 row_ror:2 row_mask:0xf bank_mask:0xf
	s_nop 1
	v_add_u32_dpp v25, v25, v25 row_ror:4 row_mask:0xf bank_mask:0xf
	s_nop 1
	v_add_u32_dpp v25, v25, v25 row_ror:8 row_mask:0xf bank_mask:0xf
	v_mov_b32_e32 v36, s87
	v_mov_b32_e32 v37, s88
	v_readlane_b32 s78, v25, 0
	v_readlane_b32 s79, v25, 16
	v_readlane_b32 s90, v25, 32
	v_readlane_b32 s91, v25, 48
	s_mov_b64 s[44:45], exec
	s_nop 2
	s_add_i32 s78, s78, s79
	s_add_i32 s90, s90, s91
	s_add_i32 s78, s78, s90
	s_lshl_b32 s20, s78, 16
	s_or_b32 s20, s20, s13
	v_mov_b32_e32 v27, s20
	s_mov_b64 exec, s[4:5]
	ds_write_b32 v36, v27
	s_mov_b64 exec, s[44:45]
.Lbis_spinP:
	ds_read_b32 v27, v37
	s_waitcnt lgkmcnt(0)
	v_readfirstlane_b32 s20, v27
	s_nop 3
	s_and_b32 s89, s20, 0xffff
	s_cmp_eq_u32 s89, s13
	s_cbranch_scc0 .Lbis_spinP
	s_lshr_b32 s20, s20, 16
	s_xor_b32 s87, s87, 4
	s_xor_b32 s88, s88, 4
	s_mov_b32 s92, s78
	s_add_i32 s78, s78, s20
	s_cmp_gt_u32 s78, 0xff
	s_cbranch_scc0 .Lbis_r2
	s_mov_b32 s85, s12
	s_mov_b32 s96, 0
	s_lshl_b32 s97, s78, 2
	s_branch .Lbis_next
.Lbis_r2:
	v_mov_b32_e32 v25, 0
	v_med3_u32 v38, v4, v26, v24
	v_med3_u32 v39, v80, v26, v24
	v_add3_u32 v25, v25, v38, v39
	v_med3_u32 v40, v79, v26, v24
	v_med3_u32 v41, v78, v26, v24
	v_add3_u32 v25, v25, v40, v41
	v_med3_u32 v42, v77, v26, v24
	v_med3_u32 v43, v76, v26, v24
	v_add3_u32 v25, v25, v42, v43
	v_med3_u32 v44, v75, v26, v24
	v_med3_u32 v45, v74, v26, v24
	v_add3_u32 v25, v25, v44, v45
	v_med3_u32 v38, v73, v26, v24
	v_med3_u32 v39, v72, v26, v24
	v_add3_u32 v25, v25, v38, v39
	v_med3_u32 v40, v71, v26, v24
	v_med3_u32 v41, v70, v26, v24
	v_add3_u32 v25, v25, v40, v41
	v_med3_u32 v42, v69, v26, v24
	v_med3_u32 v43, v68, v26, v24
	v_add3_u32 v25, v25, v42, v43
	v_med3_u32 v44, v67, v26, v24
	v_med3_u32 v45, v66, v26, v24
	v_add3_u32 v25, v25, v44, v45
	s_mov_b32 s90, 16
	s_cmp_eq_u64 s[14:15], 0
	s_cbranch_scc1 .Lbis_cntR
	v_med3_u32 v38, v2, v26, v24
	v_med3_u32 v39, v65, v26, v24
	v_add3_u32 v25, v25, v38, v39
	v_med3_u32 v40, v64, v26, v24
	v_med3_u32 v41, v49, v26, v24
	v_add3_u32 v25, v25, v40, v41
	v_med3_u32 v42, v48, v26, v24
	v_med3_u32 v43, v46, v26, v24
	v_add3_u32 v25, v25, v42, v43
	v_med3_u32 v44, v35, v26, v24
	v_med3_u32 v45, v34, v26, v24
	v_add3_u32 v25, v25, v44, v45
	v_med3_u32 v38, v33, v26, v24
	v_med3_u32 v39, v32, v26, v24
	v_add3_u32 v25, v25, v38, v39
	v_med3_u32 v40, v31, v26, v24
	v_med3_u32 v41, v30, v26, v24
	v_add3_u32 v25, v25, v40, v41
	v_med3_u32 v42, v28, v26, v24
	v_med3_u32 v43, v23, v26, v24
	v_add3_u32 v25, v25, v42, v43
	v_med3_u32 v44, v22, v26, v24
	v_med3_u32 v45, v21, v26, v24
	v_add3_u32 v25, v25, v44, v45
	s_mov_b32 s90, 32
	s_cmp_eq_u64 vcc, 0
	s_cbranch_scc1 .Lbis_cntR
	v_med3_u32 v38, v0, v26, v24
	v_med3_u32 v39, v20, v26, v24
	v_add3_u32 v25, v25, v38, v39
	v_med3_u32 v40, v19, v26, v24
	v_med3_u32 v41, v18, v26, v24
	v_add3_u32 v25, v25, v40, v41
	v_med3_u32 v42, v17, v26, v24
	v_med3_u32 v43, v16, v26, v24
	v_add3_u32 v25, v25, v42, v43
	v_med3_u32 v44, v15, v26, v24
	v_med3_u32 v45, v14, v26, v24
	v_add3_u32 v25, v25, v44, v45
	v_med3_u32 v38, v13, v26, v24
	v_med3_u32 v39, v12, v26, v24
	v_add3_u32 v25, v25, v38, v39
	v_med3_u32 v40, v11, v26, v24
	v_med3_u32 v41, v10, v26, v24
	v_add3_u32 v25, v25, v40, v41
	v_med3_u32 v42, v9, v26, v24
	v_med3_u32 v43, v8, v26, v24
	v_add3_u32 v25, v25, v42, v43
	v_med3_u32 v44, v7, v26, v24
	v_med3_u32 v45, v3, v26, v24
	v_add3_u32 v25, v25, v44, v45
	s_mov_b32 s90, 48
; #define PAIR_XCHG(SLOT, TAG, MINE, OTHER) do { const unsigned tg_ = (seq << 8) | (unsigned)(TAG); if (lane == 0) xw[w * 4 + (SLOT)] = ((MINE) << 16) | tg_; \
;             unsigned v_; do { v_ = xw[(w ^ 1) * 4 + (SLOT)]; } while ((v_ & 0xffffu) != tg_); OTHER = v_ >> 16; } while (0)
; __device__ __forceinline__ void attn_item(const Ptrs& P, unsigned char* lds, int b, int tq0, int tid) {
;     ...
;             const unsigned cand = th | (1u << bit); unsigned cnt = 0, oth;
; #pragma unroll
;             for (int k = 0; k < 4; ++k) if (16 * k < nact) {
; #pragma unroll
;                 for (int r = 16 * k; r < 16 * k + 16; ++r) cnt += (unsigned)__popcll(__ballot(k2[r] >= cand)); }
;             PAIR_XCHG(bit & 1, 1 + bit, cnt, oth);
;             cnt += oth;
;             if (cnt >= 256u) th = cand;
;             if (cnt == 256u) break;
.Lbis_cntR:
	s_sub_u32 s91, s12, 1
	s_mul_i32 s91, s91, s90
	v_subrev_u32_e32 v25, s91, v25
	s_add_i32 s13, s75, 33
	s_or_b32 s13, s86, s13
	v_add_u32_dpp v25, v25, v25 row_ror:1 row_mask:0xf bank_mask:0xf
	s_nop 1
	v_add_u32_dpp v25, v25, v25 row_ror:2 row_mask:0xf bank_mask:0xf
	s_nop 1
	v_add_u32_dpp v25, v25, v25 row_ror:4 row_mask:0xf bank_mask:0xf
	s_nop 1
	v_add_u32_dpp v25, v25, v25 row_ror:8 row_mask:0xf bank_mask:0xf
	v_mov_b32_e32 v36, s87
	v_mov_b32_e32 v37, s88
	v_readlane_b32 s78, v25, 0
	v_readlane_b32 s79, v25, 16
	v_readlane_b32 s90, v25, 32
	v_readlane_b32 s91, v25, 48
	s_mov_b64 s[44:45], exec
	s_nop 2
	s_add_i32 s78, s78, s79
	s_add_i32 s90, s90, s91
	s_add_i32 s78, s78, s90
	s_add_i32 s78, s78, s92
	s_lshl_b32 s20, s78, 16
	s_or_b32 s20, s20, s13
	v_mov_b32_e32 v27, s20
	s_mov_b64 exec, s[4:5]
	ds_write_b32 v36, v27
	s_mov_b64 exec, s[44:45]
.Lbis_spinR:
	ds_read_b32 v27, v37
	s_waitcnt lgkmcnt(0)
	v_readfirstlane_b32 s20, v27
	s_nop 3
	s_and_b32 s89, s20, 0xffff
	s_cmp_eq_u32 s89, s13
	s_cbranch_scc0 .Lbis_spinR
	s_lshr_b32 s20, s20, 16
	s_xor_b32 s87, s87, 4
	s_xor_b32 s88, s88, 4
	s_add_i32 s78, s78, s20
	s_branch .Lbis_acc
.Lbis_full:
	s_cmp_eq_u64 s[18:19], 0
	s_cbranch_scc1 .Lbis_cntF
	v_med3_u32 v38, v6, v26, v24
	v_med3_u32 v39, v95, v26, v24
	v_add3_u32 v25, v25, v38, v39
	v_med3_u32 v40, v94, v26, v24
	v_med3_u32 v41, v93, v26, v24
	v_add3_u32 v25, v25, v40, v41
	v_med3_u32 v42, v92, v26, v24
	v_med3_u32 v43, v91, v26, v24
	v_add3_u32 v25, v25, v42, v43
	v_med3_u32 v44, v90, v26, v24
	v_med3_u32 v45, v89, v26, v24
	v_add3_u32 v25, v25, v44, v45
	v_med3_u32 v38, v88, v26, v24
	v_med3_u32 v39, v87, v26, v24
	v_add3_u32 v25, v25, v38, v39
	v_med3_u32 v40, v86, v26, v24
	v_med3_u32 v41, v85, v26, v24
	v_add3_u32 v25, v25, v40, v41
	v_med3_u32 v42, v84, v26, v24
	v_med3_u32 v43, v83, v26, v24
	v_add3_u32 v25, v25, v42, v43
	v_med3_u32 v44, v82, v26, v24
	v_med3_u32 v45, v81, v26, v24
	v_add3_u32 v25, v25, v44, v45
	s_mov_b32 s90, 16
	s_cmp_eq_u64 s[16:17], 0
	s_cbranch_scc1 .Lbis_cntF
	v_med3_u32 v38, v4, v26, v24
	v_med3_u32 v39, v80, v26, v24
	v_add3_u32 v25, v25, v38, v39
	v_med3_u32 v40, v79, v26, v24
	v_med3_u32 v41, v78, v26, v24
	v_add3_u32 v25, v25, v40, v41
	v_med3_u32 v42, v77, v26, v24
	v_med3_u32 v43, v76, v26, v24
	v_add3_u32 v25, v25, v42, v43
	v_med3_u32 v44, v75, v26, v24
	v_med3_u32 v45, v74, v26, v24
	v_add3_u32 v25, v25, v44, v45
	v_med3_u32 v38, v73, v26, v24
	v_med3_u32 v39, v72, v26, v24
	v_add3_u32 v25, v25, v38, v39
	v_med3_u32 v40, v71, v26, v24
	v_med3_u32 v41, v70, v26, v24
	v_add3_u32 v25, v25, v40, v41
	v_med3_u32 v42, v69, v26, v24
	v_med3_u32 v43, v68, v26, v24
	v_add3_u32 v25, v25, v42, v43
	v_med3_u32 v44, v67, v26, v24
	v_med3_u32 v45, v66, v26, v24
	v_add3_u32 v25, v25, v44, v45
	s_mov_b32 s90, 32
	s_cmp_eq_u64 s[14:15], 0
	s_cbranch_scc1 .Lbis_cntF
	v_med3_u32 v38, v2, v26, v24
	v_med3_u32 v39, v65, v26, v24
	v_add3_u32 v25, v25, v38, v39
	v_med3_u32 v40, v64, v26, v24
	v_med3_u32 v41, v49, v26, v24
	v_add3_u32 v25, v25, v40, v41
	v_med3_u32 v42, v48, v26, v24
	v_med3_u32 v43, v46, v26, v24
	v_add3_u32 v25, v25, v42, v43
	v_med3_u32 v44, v35, v26, v24
	v_med3_u32 v45, v34, v26, v24
	v_add3_u32 v25, v25, v44, v45
	v_med3_u32 v38, v33, v26, v24
	v_med3_u32 v39, v32, v26, v24
	v_add3_u32 v25, v25, v38, v39
	v_med3_u32 v40, v31, v26, v24
	v_med3_u32 v41, v30, v26, v24
	v_add3_u32 v25, v25, v40, v41
	v_med3_u32 v42, v28, v26, v24
	v_med3_u32 v43, v23, v26, v24
	v_add3_u32 v25, v25, v42, v43
	v_med3_u32 v44, v22, v26, v24
	v_med3_u32 v45, v21, v26, v24
	v_add3_u32 v25, v25, v44, v45
	s_mov_b32 s90, 48
	s_cmp_eq_u64 vcc, 0
	s_cbranch_scc1 .Lbis_cntF
	v_med3_u32 v38, v0, v26, v24
	v_med3_u32 v39, v20, v26, v24
	v_add3_u32 v25, v25, v38, v39
	v_med3_u32 v40, v19, v26, v24
	v_med3_u32 v41, v18, v26, v24
	v_add3_u32 v25, v25, v40, v41
	v_med3_u32 v42, v17, v26, v24
	v_med3_u32 v43, v16, v26, v24
	v_add3_u32 v25, v25, v42, v43
	v_med3_u32 v44, v15, v26, v24
	v_med3_u32 v45, v14, v26, v24
	v_add3_u32 v25, v25, v44, v45
	v_med3_u32 v38, v13, v26, v24
	v_med3_u32 v39, v12, v26, v24
	v_add3_u32 v25, v25, v38, v39
	v_med3_u32 v40, v11, v26, v24
	v_med3_u32 v41, v10, v26, v24
	v_add3_u32 v25, v25, v40, v41
	v_med3_u32 v42, v9, v26, v24
	v_med3_u32 v43, v8, v26, v24
	v_add3_u32 v25, v25, v42, v43
	v_med3_u32 v44, v7, v26, v24
	v_med3_u32 v45, v3, v26, v24
	v_add3_u32 v25, v25, v44, v45
	s_mov_b32 s90, 64

; #define PAIR_XCHG(SLOT, TAG, MINE, OTHER) do { const unsigned tg_ = (seq << 8) | (unsigned)(TAG); if (lane == 0) xw[w * 4 + (SLOT)] = ((MINE) << 16) | tg_; \
;             unsigned v_; do { v_ = xw[(w ^ 1) * 4 + (SLOT)]; } while ((v_ & 0xffffu) != tg_); OTHER = v_ >> 16; } while (0)
; __device__ __forceinline__ void attn_item(const Ptrs& P, unsigned char* lds, int b, int tq0, int tid) {
;     ...
;             if (cnt >= 256u) th = cand;
;             if (cnt == 256u) break;
;         }
;         unsigned cg = 0, ce = 0;
; #pragma unroll
;         for (int k = 0; k < 4; ++k) if (16 * k < nact) {
; #pragma unroll
;             for (int r = 16 * k; r < 16 * k + 16; ++r) { cg += (k2[r] > th) ? 1u : 0u; ce += (k2[r] == th) ? 1u : 0u; } }
;         const unsigned ig = wave_incl_scan(cg, lane), ie = wave_incl_scan(ce, lane);
;         const unsigned ngt = (unsigned)__builtin_amdgcn_readlane((int)ig, 63), neq = (unsigned)__builtin_amdgcn_readlane((int)ie, 63);
;         unsigned ogt, oeq;
;         PAIR_XCHG(2, 40, ngt, ogt); PAIR_XCHG(3, 41, neq, oeq);
;         const unsigned tot_gt = ngt + ogt, quota = 256u - tot_gt;
;         unsigned pos_g = (hs ? ogt : 0u) + ig - cg, pos_e = (hs ? oeq : 0u) + ie - ce;
;         const bool any_eq = (neq + oeq) != 0u;
; #pragma unroll
;         for (int k = 0; k < 4; ++k) if (16 * k < nact) {
; #pragma unroll
;             for (int r = 16 * k; r < 16 * k + 16; ++r) { const unsigned short idx = (unsigned short)(64 * (2 * r + hs) + lane);
;                 if (k2[r] > th) { sel[qs * 256 + pos_g] = idx; ++pos_g; }
;                 if (any_eq) { if (k2[r] == th) { if (pos_e < quota) sel[qs * 256 + tot_gt + pos_e] = idx; ++pos_e; } } } }
.Lbis_spinF:
	ds_read_b32 v27, v37
	s_waitcnt lgkmcnt(0)
	v_readfirstlane_b32 s20, v27
	s_nop 3
	s_and_b32 s89, s20, 0xffff
	s_cmp_eq_u32 s89, s13
	s_cbranch_scc0 .Lbis_spinF
	s_lshr_b32 s20, s20, 16
	s_xor_b32 s87, s87, 4
	s_xor_b32 s88, s88, 4
	s_add_i32 s78, s78, s20
.Lbis_acc:
	s_cmp_gt_u32 s78, 0xff
	s_cselect_b32 s85, s12, s85
	s_cselect_b32 s96, s78, s96
	s_cselect_b32 s97, s78, s97
	s_cmp_eq_u32 s78, 0x100
	s_cbranch_scc1 .Lbis_done
.Lbis_next:
	s_cmp_eq_u32 s75, 0
	s_cbranch_scc1 .Lbis_done
	s_sub_i32 s75, s75, 1
	s_branch .Lbis_loop
	s_nop 0
	s_nop 0
	s_nop 0
	s_nop 0
	s_nop 0
.Lbis_done:
	v_mov_b32_e32 v5, s85
	s_cmp_lg_u32 s96, 0x100
	s_cbranch_scc1 .Lcmp_slow
	s_mov_b64 s[44:45], exec
	s_mov_b64 s[92:93], vcc
	s_lshl_b32 s20, s65, 9
	s_add_i32 s20, s20, 0x21000
	s_lshl_b32 s12, s64, 6
	v_or_b32_e32 v29, s12, v179
	s_add_i32 s12, s20, 0x1fe
	s_cmp_eq_u32 s64, 0
	s_cselect_b32 s88, 2, -2
	s_cselect_b32 s87, s20, s12
	v_mov_b32_e32 v38, s88
	s_xor_b32 s12, s83, 4
	s_lshl_b32 s12, s12, 2
	s_add_i32 s72, s12, 0x24000
	s_cmp_eq_u64 s[18:19], 0
	s_cbranch_scc1 .Lcmp2_done
	v_cmp_ge_u32_e64 s[78:79], v6, v5
	v_cmp_ge_u32_e64 s[90:91], v95, v5
	s_nop 0
	v_mbcnt_lo_u32_b32 v37, s78, 0
	v_mbcnt_hi_u32_b32 v37, s79, v37
	v_mad_i32_i24 v36, v37, v38, s87
	s_mov_b64 exec, s[78:79]
	ds_write_b16 v36, v29
	s_mov_b64 exec, s[44:45]
	s_bcnt1_i32_b64 s12, s[78:79]
	s_mul_i32 s12, s12, s88
	s_add_i32 s87, s87, s12
	v_cmp_ge_u32_e64 s[78:79], v94, v5
	v_or_b32_e32 v39, 0x80, v29
	v_mbcnt_lo_u32_b32 v37, s90, 0
	v_mbcnt_hi_u32_b32 v37, s91, v37
	v_mad_i32_i24 v36, v37, v38, s87
	s_mov_b64 exec, s[90:91]
	ds_write_b16 v36, v39
	s_mov_b64 exec, s[44:45]
	s_bcnt1_i32_b64 s12, s[90:91]
	s_mul_i32 s12, s12, s88
	s_add_i32 s87, s87, s12
	v_cmp_ge_u32_e64 s[90:91], v93, v5
	v_or_b32_e32 v39, 0x100, v29
	v_mbcnt_lo_u32_b32 v37, s78, 0
	v_mbcnt_hi_u32_b32 v37, s79, v37
	v_mad_i32_i24 v36, v37, v38, s87
	s_mov_b64 exec, s[78:79]
	ds_write_b16 v36, v39
	s_mov_b64 exec, s[44:45]
	s_bcnt1_i32_b64 s12, s[78:79]
	s_mul_i32 s12, s12, s88
	s_add_i32 s87, s87, s12
	v_cmp_ge_u32_e64 s[78:79], v92, v5
	v_or_b32_e32 v39, 0x180, v29
	v_mbcnt_lo_u32_b32 v37, s90, 0
	v_mbcnt_hi_u32_b32 v37, s91, v37
	v_mad_i32_i24 v36, v37, v38, s87
	s_mov_b64 exec, s[90:91]
	ds_write_b16 v36, v39
	s_mov_b64 exec, s[44:45]
	s_bcnt1_i32_b64 s12, s[90:91]
	s_mul_i32 s12, s12, s88
	s_add_i32 s87, s87, s12
	v_cmp_ge_u32_e64 s[90:91], v91, v5
	v_or_b32_e32 v39, 0x200, v29
	v_mbcnt_lo_u32_b32 v37, s78, 0
	v_mbcnt_hi_u32_b32 v37, s79, v37
	v_mad_i32_i24 v36, v37, v38, s87
	s_mov_b64 exec, s[78:79]
	ds_write_b16 v36, v39
	s_mov_b64 exec, s[44:45]
	s_bcnt1_i32_b64 s12, s[78:79]
	s_mul_i32 s12, s12, s88
	s_add_i32 s87, s87, s12
	v_cmp_ge_u32_e64 s[78:79], v90, v5
	v_or_b32_e32 v39, 0x280, v29
	v_mbcnt_lo_u32_b32 v37, s90, 0
	v_mbcnt_hi_u32_b32 v37, s91, v37
	v_mad_i32_i24 v36, v37, v38, s87
	s_mov_b64 exec, s[90:91]
	ds_write_b16 v36, v39
	s_mov_b64 exec, s[44:45]
	s_bcnt1_i32_b64 s12, s[90:91]
	s_mul_i32 s12, s12, s88
	s_add_i32 s87, s87, s12
	v_cmp_ge_u32_e64 s[90:91], v89, v5
	v_or_b32_e32 v39, 0x300, v29
	v_mbcnt_lo_u32_b32 v37, s78, 0
	v_mbcnt_hi_u32_b32 v37, s79, v37
	v_mad_i32_i24 v36, v37, v38, s87
	s_mov_b64 exec, s[78:79]
	ds_write_b16 v36, v39
	s_mov_b64 exec, s[44:45]
	s_bcnt1_i32_b64 s12, s[78:79]
	s_mul_i32 s12, s12, s88
	s_add_i32 s87, s87, s12
	v_cmp_ge_u32_e64 s[78:79], v88, v5
	v_or_b32_e32 v39, 0x380, v29
	v_mbcnt_lo_u32_b32 v37, s90, 0
	v_mbcnt_hi_u32_b32 v37, s91, v37
	v_mad_i32_i24 v36, v37, v38, s87
	s_mov_b64 exec, s[90:91]
	ds_write_b16 v36, v39
	s_mov_b64 exec, s[44:45]
	s_bcnt1_i32_b64 s12, s[90:91]
	s_mul_i32 s12, s12, s88
	s_add_i32 s87, s87, s12
	v_cmp_ge_u32_e64 s[90:91], v87, v5
	v_or_b32_e32 v39, 0x400, v29
	v_mbcnt_lo_u32_b32 v37, s78, 0
	v_mbcnt_hi_u32_b32 v37, s79, v37
	v_mad_i32_i24 v36, v37, v38, s87
	s_mov_b64 exec, s[78:79]
	ds_write_b16 v36, v39
	s_mov_b64 exec, s[44:45]
	s_bcnt1_i32_b64 s12, s[78:79]
	s_mul_i32 s12, s12, s88
	s_add_i32 s87, s87, s12
	v_cmp_ge_u32_e64 s[78:79], v86, v5
	v_or_b32_e32 v39, 0x480, v29
	v_mbcnt_lo_u32_b32 v37, s90, 0
	v_mbcnt_hi_u32_b32 v37, s91, v37
	v_mad_i32_i24 v36, v37, v38, s87
	s_mov_b64 exec, s[90:91]
	ds_write_b16 v36, v39
	s_mov_b64 exec, s[44:45]
	s_bcnt1_i32_b64 s12, s[90:91]
	s_mul_i32 s12, s12, s88
	s_add_i32 s87, s87, s12
	v_cmp_ge_u32_e64 s[90:91], v85, v5
	v_or_b32_e32 v39, 0x500, v29
	v_mbcnt_lo_u32_b32 v37, s78, 0
	v_mbcnt_hi_u32_b32 v37, s79, v37
	v_mad_i32_i24 v36, v37, v38, s87
	s_mov_b64 exec, s[78:79]
	ds_write_b16 v36, v39
	s_mov_b64 exec, s[44:45]
	s_bcnt1_i32_b64 s12, s[78:79]
	s_mul_i32 s12, s12, s88
	s_add_i32 s87, s87, s12
	v_cmp_ge_u32_e64 s[78:79], v84, v5
	v_or_b32_e32 v39, 0x580, v29
	v_mbcnt_lo_u32_b32 v37, s90, 0
	v_mbcnt_hi_u32_b32 v37, s91, v37
	v_mad_i32_i24 v36, v37, v38, s87
	s_mov_b64 exec, s[90:91]
	ds_write_b16 v36, v39
	s_mov_b64 exec, s[44:45]
	s_bcnt1_i32_b64 s12, s[90:91]
	s_mul_i32 s12, s12, s88
	s_add_i32 s87, s87, s12
	v_cmp_ge_u32_e64 s[90:91], v83, v5
	v_or_b32_e32 v39, 0x600, v29
	v_mbcnt_lo_u32_b32 v37, s78, 0
	v_mbcnt_hi_u32_b32 v37, s79, v37
	v_mad_i32_i24 v36, v37, v38, s87
	s_mov_b64 exec, s[78:79]
	ds_write_b16 v36, v39
	s_mov_b64 exec, s[44:45]
	s_bcnt1_i32_b64 s12, s[78:79]
	s_mul_i32 s12, s12, s88
	s_add_i32 s87, s87, s12
	v_cmp_ge_u32_e64 s[78:79], v82, v5
	v_or_b32_e32 v39, 0x680, v29
	v_mbcnt_lo_u32_b32 v37, s90, 0
	v_mbcnt_hi_u32_b32 v37, s91, v37
	v_mad_i32_i24 v36, v37, v38, s87
	s_mov_b64 exec, s[90:91]
	ds_write_b16 v36, v39
	s_mov_b64 exec, s[44:45]
	s_bcnt1_i32_b64 s12, s[90:91]
	s_mul_i32 s12, s12, s88
	s_add_i32 s87, s87, s12
	v_cmp_ge_u32_e64 s[90:91], v81, v5
	v_or_b32_e32 v39, 0x700, v29
	v_mbcnt_lo_u32_b32 v37, s78, 0
	v_mbcnt_hi_u32_b32 v37, s79, v37
	v_mad_i32_i24 v36, v37, v38, s87
	s_mov_b64 exec, s[78:79]
	ds_write_b16 v36, v39
	s_mov_b64 exec, s[44:45]
	s_bcnt1_i32_b64 s12, s[78:79]
	s_mul_i32 s12, s12, s88
	s_add_i32 s87, s87, s12
	v_or_b32_e32 v39, 0x780, v29
	s_nop 0
	v_mbcnt_lo_u32_b32 v37, s90, 0
	v_mbcnt_hi_u32_b32 v37, s91, v37
	v_mad_i32_i24 v36, v37, v38, s87
	s_mov_b64 exec, s[90:91]
	ds_write_b16 v36, v39
	s_mov_b64 exec, s[44:45]
	s_bcnt1_i32_b64 s12, s[90:91]
	s_mul_i32 s12, s12, s88
	s_add_i32 s87, s87, s12
	s_cmp_eq_u64 s[16:17], 0
	s_cbranch_scc1 .Lcmp2_done
; __device__ __forceinline__ void attn_item(const Ptrs& P, unsigned char* lds, int b, int tq0, int tid) {
;     ...
;         for (int k = 0; k < 4; ++k) if (16 * k < nact) {
; #pragma unroll
;             for (int r = 16 * k; r < 16 * k + 16; ++r) { const unsigned short idx = (unsigned short)(64 * (2 * r + hs) + lane);
;                 if (k2[r] > th) { sel[qs * 256 + pos_g] = idx; ++pos_g; }
;                 if (any_eq) { if (k2[r] == th) { if (pos_e < quota) sel[qs * 256 + tot_gt + pos_e] = idx; ++pos_e; } } } }
	v_cmp_ge_u32_e64 s[78:79], v4, v5
	v_cmp_ge_u32_e64 s[90:91], v80, v5
	v_or_b32_e32 v39, 0x800, v29
	v_mbcnt_lo_u32_b32 v37, s78, 0
	v_mbcnt_hi_u32_b32 v37, s79, v37
	v_mad_i32_i24 v36, v37, v38, s87
	s_mov_b64 exec, s[78:79]
	ds_write_b16 v36, v39
	s_mov_b64 exec, s[44:45]
	s_bcnt1_i32_b64 s12, s[78:79]
	s_mul_i32 s12, s12, s88
	s_add_i32 s87, s87, s12
	v_cmp_ge_u32_e64 s[78:79], v79, v5
	v_or_b32_e32 v39, 0x880, v29
	v_mbcnt_lo_u32_b32 v37, s90, 0
	v_mbcnt_hi_u32_b32 v37, s91, v37
	v_mad_i32_i24 v36, v37, v38, s87
	s_mov_b64 exec, s[90:91]
	ds_write_b16 v36, v39
	s_mov_b64 exec, s[44:45]
	s_bcnt1_i32_b64 s12, s[90:91]
	s_mul_i32 s12, s12, s88
	s_add_i32 s87, s87, s12
	v_cmp_ge_u32_e64 s[90:91], v78, v5
	v_or_b32_e32 v39, 0x900, v29
	v_mbcnt_lo_u32_b32 v37, s78, 0
	v_mbcnt_hi_u32_b32 v37, s79, v37
	v_mad_i32_i24 v36, v37, v38, s87
	s_mov_b64 exec, s[78:79]
	ds_write_b16 v36, v39
	s_mov_b64 exec, s[44:45]
	s_bcnt1_i32_b64 s12, s[78:79]
	s_mul_i32 s12, s12, s88
	s_add_i32 s87, s87, s12
	v_cmp_ge_u32_e64 s[78:79], v77, v5
	v_or_b32_e32 v39, 0x980, v29
	v_mbcnt_lo_u32_b32 v37, s90, 0
	v_mbcnt_hi_u32_b32 v37, s91, v37
	v_mad_i32_i24 v36, v37, v38, s87
	s_mov_b64 exec, s[90:91]
	ds_write_b16 v36, v39
	s_mov_b64 exec, s[44:45]
	s_bcnt1_i32_b64 s12, s[90:91]
	s_mul_i32 s12, s12, s88
	s_add_i32 s87, s87, s12
	v_cmp_ge_u32_e64 s[90:91], v76, v5
	v_or_b32_e32 v39, 0xa00, v29
	v_mbcnt_lo_u32_b32 v37, s78, 0
	v_mbcnt_hi_u32_b32 v37, s79, v37
	v_mad_i32_i24 v36, v37, v38, s87
	s_mov_b64 exec, s[78:79]
	ds_write_b16 v36, v39
	s_mov_b64 exec, s[44:45]
	s_bcnt1_i32_b64 s12, s[78:79]
	s_mul_i32 s12, s12, s88
	s_add_i32 s87, s87, s12
	v_cmp_ge_u32_e64 s[78:79], v75, v5
	v_or_b32_e32 v39, 0xa80, v29
	v_mbcnt_lo_u32_b32 v37, s90, 0
	v_mbcnt_hi_u32_b32 v37, s91, v37
	v_mad_i32_i24 v36, v37, v38, s87
	s_mov_b64 exec, s[90:91]
	ds_write_b16 v36, v39
	s_mov_b64 exec, s[44:45]
	s_bcnt1_i32_b64 s12, s[90:91]
	s_mul_i32 s12, s12, s88
	s_add_i32 s87, s87, s12
	v_cmp_ge_u32_e64 s[90:91], v74, v5
	v_or_b32_e32 v39, 0xb00, v29
	v_mbcnt_lo_u32_b32 v37, s78, 0
	v_mbcnt_hi_u32_b32 v37, s79, v37
	v_mad_i32_i24 v36, v37, v38, s87
	s_mov_b64 exec, s[78:79]
	ds_write_b16 v36, v39
	s_mov_b64 exec, s[44:45]
	s_bcnt1_i32_b64 s12, s[78:79]
	s_mul_i32 s12, s12, s88
	s_add_i32 s87, s87, s12
	v_cmp_ge_u32_e64 s[78:79], v73, v5
	v_or_b32_e32 v39, 0xb80, v29
	v_mbcnt_lo_u32_b32 v37, s90, 0
	v_mbcnt_hi_u32_b32 v37, s91, v37
	v_mad_i32_i24 v36, v37, v38, s87
	s_mov_b64 exec, s[90:91]
	ds_write_b16 v36, v39
	s_mov_b64 exec, s[44:45]
	s_bcnt1_i32_b64 s12, s[90:91]
	s_mul_i32 s12, s12, s88
	s_add_i32 s87, s87, s12
	v_cmp_ge_u32_e64 s[90:91], v72, v5
	v_or_b32_e32 v39, 0xc00, v29
	v_mbcnt_lo_u32_b32 v37, s78, 0
	v_mbcnt_hi_u32_b32 v37, s79, v37
	v_mad_i32_i24 v36, v37, v38, s87
	s_mov_b64 exec, s[78:79]
	ds_write_b16 v36, v39
	s_mov_b64 exec, s[44:45]
	s_bcnt1_i32_b64 s12, s[78:79]
	s_mul_i32 s12, s12, s88
	s_add_i32 s87, s87, s12
	v_cmp_ge_u32_e64 s[78:79], v71, v5
	v_or_b32_e32 v39, 0xc80, v29
	v_mbcnt_lo_u32_b32 v37, s90, 0
	v_mbcnt_hi_u32_b32 v37, s91, v37
	v_mad_i32_i24 v36, v37, v38, s87
	s_mov_b64 exec, s[90:91]
	ds_write_b16 v36, v39
	s_mov_b64 exec, s[44:45]
	s_bcnt1_i32_b64 s12, s[90:91]
	s_mul_i32 s12, s12, s88
	s_add_i32 s87, s87, s12
	v_cmp_ge_u32_e64 s[90:91], v70, v5
	v_or_b32_e32 v39, 0xd00, v29
	v_mbcnt_lo_u32_b32 v37, s78, 0
	v_mbcnt_hi_u32_b32 v37, s79, v37
	v_mad_i32_i24 v36, v37, v38, s87
	s_mov_b64 exec, s[78:79]
	ds_write_b16 v36, v39
	s_mov_b64 exec, s[44:45]
	s_bcnt1_i32_b64 s12, s[78:79]
	s_mul_i32 s12, s12, s88
	s_add_i32 s87, s87, s12
	v_cmp_ge_u32_e64 s[78:79], v69, v5
	v_or_b32_e32 v39, 0xd80, v29
	v_mbcnt_lo_u32_b32 v37, s90, 0
	v_mbcnt_hi_u32_b32 v37, s91, v37
	v_mad_i32_i24 v36, v37, v38, s87
	s_mov_b64 exec, s[90:91]
	ds_write_b16 v36, v39
	s_mov_b64 exec, s[44:45]
	s_bcnt1_i32_b64 s12, s[90:91]
	s_mul_i32 s12, s12, s88
	s_add_i32 s87, s87, s12
	v_cmp_ge_u32_e64 s[90:91], v68, v5
	v_or_b32_e32 v39, 0xe00, v29
	v_mbcnt_lo_u32_b32 v37, s78, 0
	v_mbcnt_hi_u32_b32 v37, s79, v37
	v_mad_i32_i24 v36, v37, v38, s87
	s_mov_b64 exec, s[78:79]
	ds_write_b16 v36, v39
	s_mov_b64 exec, s[44:45]
	s_bcnt1_i32_b64 s12, s[78:79]
	s_mul_i32 s12, s12, s88
	s_add_i32 s87, s87, s12
	v_cmp_ge_u32_e64 s[78:79], v67, v5
	v_or_b32_e32 v39, 0xe80, v29
	v_mbcnt_lo_u32_b32 v37, s90, 0
	v_mbcnt_hi_u32_b32 v37, s91, v37
	v_mad_i32_i24 v36, v37, v38, s87
	s_mov_b64 exec, s[90:91]
	ds_write_b16 v36, v39
	s_mov_b64 exec, s[44:45]
	s_bcnt1_i32_b64 s12, s[90:91]
	s_mul_i32 s12, s12, s88
	s_add_i32 s87, s87, s12
	v_cmp_ge_u32_e64 s[90:91], v66, v5
	v_or_b32_e32 v39, 0xf00, v29
	v_mbcnt_lo_u32_b32 v37, s78, 0
	v_mbcnt_hi_u32_b32 v37, s79, v37
	v_mad_i32_i24 v36, v37, v38, s87
	s_mov_b64 exec, s[78:79]
	ds_write_b16 v36, v39
	s_mov_b64 exec, s[44:45]
	s_bcnt1_i32_b64 s12, s[78:79]
	s_mul_i32 s12, s12, s88
	s_add_i32 s87, s87, s12
	v_or_b32_e32 v39, 0xf80, v29
	s_nop 0
	v_mbcnt_lo_u32_b32 v37, s90, 0
	v_mbcnt_hi_u32_b32 v37, s91, v37
	v_mad_i32_i24 v36, v37, v38, s87
	s_mov_b64 exec, s[90:91]
	ds_write_b16 v36, v39
	s_mov_b64 exec, s[44:45]
	s_bcnt1_i32_b64 s12, s[90:91]
	s_mul_i32 s12, s12, s88
	s_add_i32 s87, s87, s12
	s_cmp_eq_u64 s[14:15], 0
	s_cbranch_scc1 .Lcmp2_done
; __device__ __forceinline__ void attn_item(const Ptrs& P, unsigned char* lds, int b, int tq0, int tid) {
;     ...
;         for (int k = 0; k < 4; ++k) if (16 * k < nact) {
; #pragma unroll
;             for (int r = 16 * k; r < 16 * k + 16; ++r) { const unsigned short idx = (unsigned short)(64 * (2 * r + hs) + lane);
;                 if (k2[r] > th) { sel[qs * 256 + pos_g] = idx; ++pos_g; }
;                 if (any_eq) { if (k2[r] == th) { if (pos_e < quota) sel[qs * 256 + tot_gt + pos_e] = idx; ++pos_e; } } } }
	v_cmp_ge_u32_e64 s[78:79], v2, v5
	v_cmp_ge_u32_e64 s[90:91], v65, v5
	v_or_b32_e32 v39, 0x1000, v29
	v_mbcnt_lo_u32_b32 v37, s78, 0
	v_mbcnt_hi_u32_b32 v37, s79, v37
	v_mad_i32_i24 v36, v37, v38, s87
	s_mov_b64 exec, s[78:79]
	ds_write_b16 v36, v39
	s_mov_b64 exec, s[44:45]
	s_bcnt1_i32_b64 s12, s[78:79]
	s_mul_i32 s12, s12, s88
	s_add_i32 s87, s87, s12
	v_cmp_ge_u32_e64 s[78:79], v64, v5
	v_or_b32_e32 v39, 0x1080, v29
	v_mbcnt_lo_u32_b32 v37, s90, 0
	v_mbcnt_hi_u32_b32 v37, s91, v37
	v_mad_i32_i24 v36, v37, v38, s87
	s_mov_b64 exec, s[90:91]
	ds_write_b16 v36, v39
	s_mov_b64 exec, s[44:45]
	s_bcnt1_i32_b64 s12, s[90:91]
	s_mul_i32 s12, s12, s88
	s_add_i32 s87, s87, s12
	v_cmp_ge_u32_e64 s[90:91], v49, v5
	v_or_b32_e32 v39, 0x1100, v29
	v_mbcnt_lo_u32_b32 v37, s78, 0
	v_mbcnt_hi_u32_b32 v37, s79, v37
	v_mad_i32_i24 v36, v37, v38, s87
	s_mov_b64 exec, s[78:79]
	ds_write_b16 v36, v39
	s_mov_b64 exec, s[44:45]
	s_bcnt1_i32_b64 s12, s[78:79]
	s_mul_i32 s12, s12, s88
	s_add_i32 s87, s87, s12
	v_cmp_ge_u32_e64 s[78:79], v48, v5
	v_or_b32_e32 v39, 0x1180, v29
	v_mbcnt_lo_u32_b32 v37, s90, 0
	v_mbcnt_hi_u32_b32 v37, s91, v37
	v_mad_i32_i24 v36, v37, v38, s87
	s_mov_b64 exec, s[90:91]
	ds_write_b16 v36, v39
	s_mov_b64 exec, s[44:45]
	s_bcnt1_i32_b64 s12, s[90:91]
	s_mul_i32 s12, s12, s88
	s_add_i32 s87, s87, s12
	v_cmp_ge_u32_e64 s[90:91], v46, v5
	v_or_b32_e32 v39, 0x1200, v29
	v_mbcnt_lo_u32_b32 v37, s78, 0
	v_mbcnt_hi_u32_b32 v37, s79, v37
	v_mad_i32_i24 v36, v37, v38, s87
	s_mov_b64 exec, s[78:79]
	ds_write_b16 v36, v39
	s_mov_b64 exec, s[44:45]
	s_bcnt1_i32_b64 s12, s[78:79]
	s_mul_i32 s12, s12, s88
	s_add_i32 s87, s87, s12
	v_cmp_ge_u32_e64 s[78:79], v35, v5
	v_or_b32_e32 v39, 0x1280, v29
	v_mbcnt_lo_u32_b32 v37, s90, 0
	v_mbcnt_hi_u32_b32 v37, s91, v37
	v_mad_i32_i24 v36, v37, v38, s87
	s_mov_b64 exec, s[90:91]
	ds_write_b16 v36, v39
	s_mov_b64 exec, s[44:45]
	s_bcnt1_i32_b64 s12, s[90:91]
	s_mul_i32 s12, s12, s88
	s_add_i32 s87, s87, s12
	v_cmp_ge_u32_e64 s[90:91], v34, v5
	v_or_b32_e32 v39, 0x1300, v29
	v_mbcnt_lo_u32_b32 v37, s78, 0
	v_mbcnt_hi_u32_b32 v37, s79, v37
	v_mad_i32_i24 v36, v37, v38, s87
	s_mov_b64 exec, s[78:79]
	ds_write_b16 v36, v39
	s_mov_b64 exec, s[44:45]
	s_bcnt1_i32_b64 s12, s[78:79]
	s_mul_i32 s12, s12, s88
	s_add_i32 s87, s87, s12
	v_cmp_ge_u32_e64 s[78:79], v33, v5
	v_or_b32_e32 v39, 0x1380, v29
	v_mbcnt_lo_u32_b32 v37, s90, 0
	v_mbcnt_hi_u32_b32 v37, s91, v37
	v_mad_i32_i24 v36, v37, v38, s87
	s_mov_b64 exec, s[90:91]
	ds_write_b16 v36, v39
	s_mov_b64 exec, s[44:45]
	s_bcnt1_i32_b64 s12, s[90:91]
	s_mul_i32 s12, s12, s88
	s_add_i32 s87, s87, s12
	v_cmp_ge_u32_e64 s[90:91], v32, v5
	v_or_b32_e32 v39, 0x1400, v29
	v_mbcnt_lo_u32_b32 v37, s78, 0
	v_mbcnt_hi_u32_b32 v37, s79, v37
	v_mad_i32_i24 v36, v37, v38, s87
	s_mov_b64 exec, s[78:79]
	ds_write_b16 v36, v39
	s_mov_b64 exec, s[44:45]
	s_bcnt1_i32_b64 s12, s[78:79]
	s_mul_i32 s12, s12, s88
	s_add_i32 s87, s87, s12
	v_cmp_ge_u32_e64 s[78:79], v31, v5
	v_or_b32_e32 v39, 0x1480, v29
	v_mbcnt_lo_u32_b32 v37, s90, 0
	v_mbcnt_hi_u32_b32 v37, s91, v37
	v_mad_i32_i24 v36, v37, v38, s87
	s_mov_b64 exec, s[90:91]
	ds_write_b16 v36, v39
	s_mov_b64 exec, s[44:45]
	s_bcnt1_i32_b64 s12, s[90:91]
	s_mul_i32 s12, s12, s88
	s_add_i32 s87, s87, s12
	v_cmp_ge_u32_e64 s[90:91], v30, v5
	v_or_b32_e32 v39, 0x1500, v29
	v_mbcnt_lo_u32_b32 v37, s78, 0
	v_mbcnt_hi_u32_b32 v37, s79, v37
	v_mad_i32_i24 v36, v37, v38, s87
	s_mov_b64 exec, s[78:79]
	ds_write_b16 v36, v39
	s_mov_b64 exec, s[44:45]
	s_bcnt1_i32_b64 s12, s[78:79]
	s_mul_i32 s12, s12, s88
	s_add_i32 s87, s87, s12
	v_cmp_ge_u32_e64 s[78:79], v28, v5
	v_or_b32_e32 v39, 0x1580, v29
	v_mbcnt_lo_u32_b32 v37, s90, 0
	v_mbcnt_hi_u32_b32 v37, s91, v37
	v_mad_i32_i24 v36, v37, v38, s87
	s_mov_b64 exec, s[90:91]
	ds_write_b16 v36, v39
	s_mov_b64 exec, s[44:45]
	s_bcnt1_i32_b64 s12, s[90:91]
	s_mul_i32 s12, s12, s88
	s_add_i32 s87, s87, s12
	v_cmp_ge_u32_e64 s[90:91], v23, v5
	v_or_b32_e32 v39, 0x1600, v29
	v_mbcnt_lo_u32_b32 v37, s78, 0
	v_mbcnt_hi_u32_b32 v37, s79, v37
	v_mad_i32_i24 v36, v37, v38, s87
	s_mov_b64 exec, s[78:79]
	ds_write_b16 v36, v39
	s_mov_b64 exec, s[44:45]
	s_bcnt1_i32_b64 s12, s[78:79]
	s_mul_i32 s12, s12, s88
	s_add_i32 s87, s87, s12
	v_cmp_ge_u32_e64 s[78:79], v22, v5
	v_or_b32_e32 v39, 0x1680, v29
	v_mbcnt_lo_u32_b32 v37, s90, 0
	v_mbcnt_hi_u32_b32 v37, s91, v37
	v_mad_i32_i24 v36, v37, v38, s87
	s_mov_b64 exec, s[90:91]
	ds_write_b16 v36, v39
	s_mov_b64 exec, s[44:45]
	s_bcnt1_i32_b64 s12, s[90:91]
	s_mul_i32 s12, s12, s88
	s_add_i32 s87, s87, s12
	v_cmp_ge_u32_e64 s[90:91], v21, v5
	v_or_b32_e32 v39, 0x1700, v29
	v_mbcnt_lo_u32_b32 v37, s78, 0
	v_mbcnt_hi_u32_b32 v37, s79, v37
	v_mad_i32_i24 v36, v37, v38, s87
	s_mov_b64 exec, s[78:79]
	ds_write_b16 v36, v39
	s_mov_b64 exec, s[44:45]
	s_bcnt1_i32_b64 s12, s[78:79]
	s_mul_i32 s12, s12, s88
	s_add_i32 s87, s87, s12
	v_or_b32_e32 v39, 0x1780, v29
	s_nop 0
	v_mbcnt_lo_u32_b32 v37, s90, 0
	v_mbcnt_hi_u32_b32 v37, s91, v37
	v_mad_i32_i24 v36, v37, v38, s87
	s_mov_b64 exec, s[90:91]
	ds_write_b16 v36, v39
	s_mov_b64 exec, s[44:45]
	s_bcnt1_i32_b64 s12, s[90:91]
	s_mul_i32 s12, s12, s88
	s_add_i32 s87, s87, s12
	s_cmp_eq_u64 s[92:93], 0
	s_cbranch_scc1 .Lcmp2_done
; __device__ __forceinline__ void attn_item(const Ptrs& P, unsigned char* lds, int b, int tq0, int tid) {
;     ...
;         for (int k = 0; k < 4; ++k) if (16 * k < nact) {
; #pragma unroll
;             for (int r = 16 * k; r < 16 * k + 16; ++r) { const unsigned short idx = (unsigned short)(64 * (2 * r + hs) + lane);
;                 if (k2[r] > th) { sel[qs * 256 + pos_g] = idx; ++pos_g; }
;                 if (any_eq) { if (k2[r] == th) { if (pos_e < quota) sel[qs * 256 + tot_gt + pos_e] = idx; ++pos_e; } } } }
	v_cmp_ge_u32_e64 s[78:79], v0, v5
	v_cmp_ge_u32_e64 s[90:91], v20, v5
	v_or_b32_e32 v39, 0x1800, v29
	v_mbcnt_lo_u32_b32 v37, s78, 0
	v_mbcnt_hi_u32_b32 v37, s79, v37
	v_mad_i32_i24 v36, v37, v38, s87
	s_mov_b64 exec, s[78:79]
	ds_write_b16 v36, v39
	s_mov_b64 exec, s[44:45]
	s_bcnt1_i32_b64 s12, s[78:79]
	s_mul_i32 s12, s12, s88
	s_add_i32 s87, s87, s12
	v_cmp_ge_u32_e64 s[78:79], v19, v5
	v_or_b32_e32 v39, 0x1880, v29
	v_mbcnt_lo_u32_b32 v37, s90, 0
	v_mbcnt_hi_u32_b32 v37, s91, v37
	v_mad_i32_i24 v36, v37, v38, s87
	s_mov_b64 exec, s[90:91]
	ds_write_b16 v36, v39
	s_mov_b64 exec, s[44:45]
	s_bcnt1_i32_b64 s12, s[90:91]
	s_mul_i32 s12, s12, s88
	s_add_i32 s87, s87, s12
	v_cmp_ge_u32_e64 s[90:91], v18, v5
	v_or_b32_e32 v39, 0x1900, v29
	v_mbcnt_lo_u32_b32 v37, s78, 0
	v_mbcnt_hi_u32_b32 v37, s79, v37
	v_mad_i32_i24 v36, v37, v38, s87
	s_mov_b64 exec, s[78:79]
	ds_write_b16 v36, v39
	s_mov_b64 exec, s[44:45]
	s_bcnt1_i32_b64 s12, s[78:79]
	s_mul_i32 s12, s12, s88
	s_add_i32 s87, s87, s12
	v_cmp_ge_u32_e64 s[78:79], v17, v5
	v_or_b32_e32 v39, 0x1980, v29
	v_mbcnt_lo_u32_b32 v37, s90, 0
	v_mbcnt_hi_u32_b32 v37, s91, v37
	v_mad_i32_i24 v36, v37, v38, s87
	s_mov_b64 exec, s[90:91]
	ds_write_b16 v36, v39
	s_mov_b64 exec, s[44:45]
	s_bcnt1_i32_b64 s12, s[90:91]
	s_mul_i32 s12, s12, s88
	s_add_i32 s87, s87, s12
	v_cmp_ge_u32_e64 s[90:91], v16, v5
	v_or_b32_e32 v39, 0x1a00, v29
	v_mbcnt_lo_u32_b32 v37, s78, 0
	v_mbcnt_hi_u32_b32 v37, s79, v37
	v_mad_i32_i24 v36, v37, v38, s87
	s_mov_b64 exec, s[78:79]
	ds_write_b16 v36, v39
	s_mov_b64 exec, s[44:45]
	s_bcnt1_i32_b64 s12, s[78:79]
	s_mul_i32 s12, s12, s88
	s_add_i32 s87, s87, s12
	v_cmp_ge_u32_e64 s[78:79], v15, v5
	v_or_b32_e32 v39, 0x1a80, v29
	v_mbcnt_lo_u32_b32 v37, s90, 0
	v_mbcnt_hi_u32_b32 v37, s91, v37
	v_mad_i32_i24 v36, v37, v38, s87
	s_mov_b64 exec, s[90:91]
	ds_write_b16 v36, v39
	s_mov_b64 exec, s[44:45]
	s_bcnt1_i32_b64 s12, s[90:91]
	s_mul_i32 s12, s12, s88
	s_add_i32 s87, s87, s12
	v_cmp_ge_u32_e64 s[90:91], v14, v5
	v_or_b32_e32 v39, 0x1b00, v29
	v_mbcnt_lo_u32_b32 v37, s78, 0
	v_mbcnt_hi_u32_b32 v37, s79, v37
	v_mad_i32_i24 v36, v37, v38, s87
	s_mov_b64 exec, s[78:79]
	ds_write_b16 v36, v39
	s_mov_b64 exec, s[44:45]
	s_bcnt1_i32_b64 s12, s[78:79]
	s_mul_i32 s12, s12, s88
	s_add_i32 s87, s87, s12
	v_cmp_ge_u32_e64 s[78:79], v13, v5
	v_or_b32_e32 v39, 0x1b80, v29
	v_mbcnt_lo_u32_b32 v37, s90, 0
	v_mbcnt_hi_u32_b32 v37, s91, v37
	v_mad_i32_i24 v36, v37, v38, s87
	s_mov_b64 exec, s[90:91]
	ds_write_b16 v36, v39
	s_mov_b64 exec, s[44:45]
	s_bcnt1_i32_b64 s12, s[90:91]
	s_mul_i32 s12, s12, s88
	s_add_i32 s87, s87, s12
	v_cmp_ge_u32_e64 s[90:91], v12, v5
	v_or_b32_e32 v39, 0x1c00, v29
	v_mbcnt_lo_u32_b32 v37, s78, 0
	v_mbcnt_hi_u32_b32 v37, s79, v37
	v_mad_i32_i24 v36, v37, v38, s87
	s_mov_b64 exec, s[78:79]
	ds_write_b16 v36, v39
	s_mov_b64 exec, s[44:45]
	s_bcnt1_i32_b64 s12, s[78:79]
	s_mul_i32 s12, s12, s88
	s_add_i32 s87, s87, s12
	v_cmp_ge_u32_e64 s[78:79], v11, v5
	v_or_b32_e32 v39, 0x1c80, v29
	v_mbcnt_lo_u32_b32 v37, s90, 0
	v_mbcnt_hi_u32_b32 v37, s91, v37
	v_mad_i32_i24 v36, v37, v38, s87
	s_mov_b64 exec, s[90:91]
	ds_write_b16 v36, v39
	s_mov_b64 exec, s[44:45]
	s_bcnt1_i32_b64 s12, s[90:91]
	s_mul_i32 s12, s12, s88
	s_add_i32 s87, s87, s12
	v_cmp_ge_u32_e64 s[90:91], v10, v5
	v_or_b32_e32 v39, 0x1d00, v29
	v_mbcnt_lo_u32_b32 v37, s78, 0
	v_mbcnt_hi_u32_b32 v37, s79, v37
	v_mad_i32_i24 v36, v37, v38, s87
	s_mov_b64 exec, s[78:79]
	ds_write_b16 v36, v39
	s_mov_b64 exec, s[44:45]
	s_bcnt1_i32_b64 s12, s[78:79]
	s_mul_i32 s12, s12, s88
	s_add_i32 s87, s87, s12
	v_cmp_ge_u32_e64 s[78:79], v9, v5
	v_or_b32_e32 v39, 0x1d80, v29
	v_mbcnt_lo_u32_b32 v37, s90, 0
	v_mbcnt_hi_u32_b32 v37, s91, v37
	v_mad_i32_i24 v36, v37, v38, s87
	s_mov_b64 exec, s[90:91]
	ds_write_b16 v36, v39
	s_mov_b64 exec, s[44:45]
	s_bcnt1_i32_b64 s12, s[90:91]
	s_mul_i32 s12, s12, s88
	s_add_i32 s87, s87, s12
	v_cmp_ge_u32_e64 s[90:91], v8, v5
	v_or_b32_e32 v39, 0x1e00, v29
	v_mbcnt_lo_u32_b32 v37, s78, 0
	v_mbcnt_hi_u32_b32 v37, s79, v37
	v_mad_i32_i24 v36, v37, v38, s87
	s_mov_b64 exec, s[78:79]
	ds_write_b16 v36, v39
	s_mov_b64 exec, s[44:45]
	s_bcnt1_i32_b64 s12, s[78:79]
	s_mul_i32 s12, s12, s88
	s_add_i32 s87, s87, s12
	v_cmp_ge_u32_e64 s[78:79], v7, v5
	v_or_b32_e32 v39, 0x1e80, v29
	v_mbcnt_lo_u32_b32 v37, s90, 0
	v_mbcnt_hi_u32_b32 v37, s91, v37
	v_mad_i32_i24 v36, v37, v38, s87
	s_mov_b64 exec, s[90:91]
	ds_write_b16 v36, v39
	s_mov_b64 exec, s[44:45]
	s_bcnt1_i32_b64 s12, s[90:91]
	s_mul_i32 s12, s12, s88
	s_add_i32 s87, s87, s12
	v_cmp_ge_u32_e64 s[90:91], v3, v5
	v_or_b32_e32 v39, 0x1f00, v29
	v_mbcnt_lo_u32_b32 v37, s78, 0
	v_mbcnt_hi_u32_b32 v37, s79, v37
	v_mad_i32_i24 v36, v37, v38, s87
	s_mov_b64 exec, s[78:79]
	ds_write_b16 v36, v39
	s_mov_b64 exec, s[44:45]
	s_bcnt1_i32_b64 s12, s[78:79]
	s_mul_i32 s12, s12, s88
	s_add_i32 s87, s87, s12
	v_or_b32_e32 v39, 0x1f80, v29
	s_nop 0
	v_mbcnt_lo_u32_b32 v37, s90, 0
	v_mbcnt_hi_u32_b32 v37, s91, v37
	v_mad_i32_i24 v36, v37, v38, s87
	s_mov_b64 exec, s[90:91]
	ds_write_b16 v36, v39
	s_mov_b64 exec, s[44:45]
	s_bcnt1_i32_b64 s12, s[90:91]
	s_mul_i32 s12, s12, s88
	s_add_i32 s87, s87, s12
